# FFN-up: first K-iteration waits no longer drain the previous unit's epilogue stores (counted vmcnt 10/14), phase prologue drains to 0
# speedup vs baseline: 1.0113x; 1.0015x over previous
; #define PG8_STAGE(bufoff, gbase, voff) do { _Pragma("unroll") for (int _i = 0; _i < 2; ++_i) \
;         __builtin_amdgcn_global_load_lds((const unsigned*)((const char*)(gbase) + (voff)[_i]), (LAS unsigned*)(lds + (bufoff) + ldsw + _i * 8192), 16, 0, 0); } while (0)
; #define PG8_WAIT_V(n) asm volatile("s_waitcnt vmcnt(" #n ")" ::: "memory")
; #define PG8_BAR __builtin_amdgcn_s_barrier()
; template <class Epi, class Sched>
; __device__ __forceinline__ void gemm_phase(const int tid, LAS unsigned char* lds, const int lda, const int ldb, const int K, const Sched& S, const Epi& E) {
;     ...
;     if (!S.next(0, cur)) return;
;     f32x4 acc[2][2][4][2];
;     float es0 = 0.f, es1 = 0.f;
;     E.pre(cur, wr, wc, fr, fq, es0, es1);
;     E.init(acc, cur, wr, wc, fr, fq);
;     bf16x8 At[4][2], B0[2][2], B1[2][2];
;     const char* cA = cur.a; const char* cB = cur.b;
;     PG8_STAGE(PG8_SB(0, 0), cB, voffB); PG8_STAGE(PG8_SB(0, 1), cB + hstepB, voffB); PG8_STAGE(PG8_SA(0, 0), cA, voffA); PG8_STAGE(PG8_SA(0, 1), cA + hstepA, voffA);
;     if (wr == 1) PG8_BAR;
;     PG8_WAIT_V(2); PG8_BAR;
;     PG8_STAGE(PG8_SB(1, 0), cB + kstep, voffB); PG8_STAGE(PG8_SA(1, 0), cA + kstep, voffA); PG8_STAGE(PG8_SB(1, 1), cB + hstepB + kstep, voffB);
;     PG8_WAIT_V(6); PG8_BAR;
; __device__ __forceinline__ float row_rstd(const float* SS, int row) {
;     const f32x4* p = (const f32x4*)(SS + (size_t)row * 32);
;     float s = 0.f;
; #pragma unroll
;     for (int j = 0; j < 8; ++j) { const f32x4 a = p[j]; s += (a[0] + a[1]) + (a[2] + a[3]); }
;     return rsqrtf(s * (1.f / 1024.f) + EPS);
.LBB0_889:
	s_waitcnt vmcnt(0)
	v_mov_b32_e32 v80, v60
	v_mov_b32_e32 v81, v52
	v_mov_b32_e32 v52, v61
	v_mov_b32_e32 v60, v62
	v_mov_b32_e32 v61, v54
	v_mov_b32_e32 v54, v63
	v_pk_add_f32 v[52:53], v[80:81], v[52:53]
	v_pk_add_f32 v[54:55], v[60:61], v[54:55]
	s_lshl_b32 s27, s27, 5
	v_pk_add_f32 v[52:53], v[52:53], v[54:55]
	v_mov_b32_e32 v54, v56
	v_mov_b32_e32 v55, v44
	v_mov_b32_e32 v44, v57
	v_pk_add_f32 v[44:45], v[54:55], v[44:45]
	v_mov_b32_e32 v54, v58
	v_mov_b32_e32 v55, v46
	v_mov_b32_e32 v46, v59
	v_pk_add_f32 v[46:47], v[54:55], v[46:47]
	s_and_b32 s38, s27, 0x60
	v_pk_add_f32 v[44:45], v[44:45], v[46:47]
	v_mov_b32_e32 v46, v48
	v_mov_b32_e32 v47, v36
	v_mov_b32_e32 v36, v49
	v_pk_add_f32 v[36:37], v[46:47], v[36:37]
	v_mov_b32_e32 v46, v50
	v_mov_b32_e32 v47, v38
	v_mov_b32_e32 v38, v51
	v_pk_add_f32 v[38:39], v[46:47], v[38:39]
	s_add_i32 m0, s29, 0x18000
	v_pk_add_f32 v[36:37], v[36:37], v[38:39]
	v_mov_b32_e32 v38, v40
	v_mov_b32_e32 v39, v28
	v_mov_b32_e32 v28, v41
	v_pk_add_f32 v[28:29], v[38:39], v[28:29]
	v_mov_b32_e32 v38, v42
	v_mov_b32_e32 v39, v30
	v_mov_b32_e32 v30, v43
	v_pk_add_f32 v[30:31], v[38:39], v[30:31]
	s_lshl_b32 s24, s36, 13
	v_pk_add_f32 v[28:29], v[28:29], v[30:31]
	v_mov_b32_e32 v30, v32
	v_mov_b32_e32 v31, v20
	v_mov_b32_e32 v20, v33
	v_pk_add_f32 v[20:21], v[30:31], v[20:21]
	v_mov_b32_e32 v30, v34
	v_mov_b32_e32 v31, v22
	v_mov_b32_e32 v22, v35
	v_pk_add_f32 v[22:23], v[30:31], v[22:23]
	s_lshl_b32 s39, s38, 7
	v_pk_add_f32 v[20:21], v[20:21], v[22:23]
	v_mov_b32_e32 v22, v24
	v_mov_b32_e32 v23, v16
	v_mov_b32_e32 v16, v25
	v_pk_add_f32 v[16:17], v[22:23], v[16:17]
	v_mov_b32_e32 v22, v26
	v_mov_b32_e32 v23, v18
	v_mov_b32_e32 v18, v27
	v_pk_add_f32 v[18:19], v[22:23], v[18:19]
	s_waitcnt vmcnt(2)
	s_barrier
	v_pk_add_f32 v[16:17], v[16:17], v[18:19]
	v_lshl_add_u64 v[18:19], v[70:71], 0, s[6:7]
	global_load_lds_dwordx4 v[18:19], off
	v_lshl_add_u64 v[18:19], v[68:69], 0, s[6:7]
	s_add_i32 m0, s29, 0x1a000
	s_add_i32 s58, s29, 0x8000
	s_add_i32 s59, s29, 0xa000
	global_load_lds_dwordx4 v[18:19], off
	v_lshl_add_u64 v[18:19], v[64:65], 0, s[6:7]
	s_mov_b32 m0, s58
	s_add_u32 s36, s52, 0x40080
	global_load_lds_dwordx4 v[18:19], off
	v_lshl_add_u64 v[18:19], v[66:67], 0, s[6:7]
	s_mov_b32 m0, s59
	s_addc_u32 s37, s53, 0
	global_load_lds_dwordx4 v[18:19], off
	s_add_i32 m0, s29, 0x1c000
	v_lshl_add_u64 v[18:19], s[36:37], 0, v[132:133]
	global_load_lds_dwordx4 v[18:19], off
	v_lshl_add_u64 v[18:19], s[36:37], 0, v[128:129]
	s_add_i32 m0, s29, 0x1e000
	v_pk_add_f32 v[52:53], v[52:53], 0 op_sel_hi:[1,0]
	global_load_lds_dwordx4 v[18:19], off
	v_pk_add_f32 v[44:45], v[52:53], v[44:45]
	v_mov_b32_e32 v18, v12
	v_mov_b32_e32 v19, v4
	v_mov_b32_e32 v4, v13
	v_mov_b32_e32 v12, v14
	v_mov_b32_e32 v13, v6
	v_mov_b32_e32 v6, v15
	v_pk_add_f32 v[36:37], v[44:45], v[36:37]
	v_pk_add_f32 v[4:5], v[18:19], v[4:5]
	v_pk_add_f32 v[6:7], v[12:13], v[6:7]
	v_pk_add_f32 v[28:29], v[36:37], v[28:29]
	v_pk_add_f32 v[4:5], v[4:5], v[6:7]
	v_mov_b32_e32 v6, v8
	v_mov_b32_e32 v7, v0
	v_mov_b32_e32 v0, v9
	v_pk_add_f32 v[20:21], v[28:29], v[20:21]
	v_pk_add_f32 v[0:1], v[6:7], v[0:1]
	v_mov_b32_e32 v6, v10
	v_mov_b32_e32 v7, v2
	v_mov_b32_e32 v2, v11
	v_pk_add_f32 v[16:17], v[20:21], v[16:17]
	v_pk_add_f32 v[2:3], v[6:7], v[2:3]
	v_pk_add_f32 v[4:5], v[16:17], v[4:5]
	v_pk_add_f32 v[0:1], v[0:1], v[2:3]
	s_mov_b32 s14, 0x3a800000
	v_pk_add_f32 v[0:1], v[4:5], v[0:1]
	s_sext_i32_i16 s27, s2
	v_pk_fma_f32 v[0:1], v[0:1], s[14:15], v[170:171] op_sel_hi:[1,0,0]
	s_mov_b32 s2, 0x45800000
	v_mul_f32_e32 v2, 0x4b800000, v1
	v_cmp_gt_f32_e32 vcc, s33, v1
	v_cmp_gt_f32_e64 s[36:37], s33, v0
	v_or_b32_e32 v144, s4, v142
	v_cndmask_b32_e32 v1, v1, v2, vcc
	v_mul_f32_e32 v2, 0x4b800000, v0
	v_cndmask_b32_e64 v0, v0, v2, s[36:37]
	v_rsq_f32_e32 v1, v1
	v_rsq_f32_e32 v0, v0
	v_lshlrev_b32_e32 v145, 2, v142
	s_cmp_gt_i32 s13, 0
	s_waitcnt vmcnt(0)
	v_pk_mul_f32 v[2:3], v[0:1], s[2:3] op_sel_hi:[1,0]
	s_movk_i32 s2, 0x3c0
	v_cndmask_b32_e32 v141, v1, v3, vcc
	v_cndmask_b32_e64 v140, v0, v2, s[36:37]
	v_lshlrev_b32_e32 v1, 6, v144
	v_lshlrev_b32_e32 v2, 2, v144
	v_and_or_b32 v1, v1, s2, v75
	v_and_b32_e32 v2, 32, v2
	v_bitop3_b32 v1, v1, s24, v2 bitop3:0xde
	v_lshl_or_b32 v2, v142, 6, v75
	v_and_b32_e32 v3, 32, v145
	v_bitop3_b32 v146, s39, v2, v3 bitop3:0xf6
	v_lshlrev_b32_e32 v2, 14, v78
	v_and_b32_e32 v2, 0xffff8000, v2
	v_lshl_add_u32 v2, v77, 11, v2
	v_and_b32_e32 v3, 1, v78
	v_lshl_or_b32 v2, v3, 6, v2
	v_lshl_add_u32 v136, v79, 1, v2
	v_lshlrev_b32_e32 v2, 14, v72
	v_and_b32_e32 v2, 0xffff8000, v2
	s_cselect_b64 s[40:41], -1, 0
	s_add_i32 s61, s13, -2
	v_lshl_add_u32 v2, v73, 11, v2
	v_and_b32_e32 v3, 1, v72
	v_lshlrev_b32_e32 v0, 3, v76
	s_cmpk_lt_u32 s3, 0x100
	v_lshl_or_b32 v2, v3, 6, v2
	s_mov_b32 s60, 0
	s_cselect_b64 s[42:43], -1, 0
	v_or_b32_e32 v147, 16, v144
	v_or_b32_e32 v148, 64, v145
	v_or_b32_e32 v149, 32, v144
	v_or_b32_e32 v150, 0x80, v145
	v_or_b32_e32 v151, 48, v144
	v_or_b32_e32 v152, 0xc0, v145
	s_ashr_i32 s62, s30, 31
	v_mov_b32_e32 v137, v169
	v_lshl_add_u32 v138, v74, 1, v2
	v_mov_b32_e32 v139, v169
	v_add_u32_e32 v153, 0, v1
	s_lshl_b32 s4, s38, 1
	v_lshlrev_b32_e32 v168, 1, v0
	s_barrier
	s_branch .LBB0_892

; #define PG8_STAGE(bufoff, gbase, voff) do { _Pragma("unroll") for (int _i = 0; _i < 2; ++_i) \
;         __builtin_amdgcn_global_load_lds((const unsigned*)((const char*)(gbase) + (voff)[_i]), (LAS unsigned*)(lds + (bufoff) + ldsw + _i * 8192), 16, 0, 0); } while (0)
; #define PG8_LDA(dst, b, h) do { _Pragma("unroll") for (int m = 0; m < 4; ++m) _Pragma("unroll") for (int k = 0; k < 2; ++k) dst[m][k] = *(const LAS bf16x8*)(lds + PG8_SA(b, h) + aoff + m * 2048 + k * 1024); } while (0)
; #define PG8_LDB(dst, b, h) do { _Pragma("unroll") for (int n = 0; n < 2; ++n) _Pragma("unroll") for (int k = 0; k < 2; ++k) dst[n][k] = *(const LAS bf16x8*)(lds + PG8_SB(b, h) + boff + n * 2048 + k * 1024); } while (0)
; #define PG8_MMA(ai, bj, At, Bt) do { __builtin_amdgcn_s_setprio(1); _Pragma("unroll") for (int m = 0; m < 4; ++m) _Pragma("unroll") for (int n = 0; n < 2; ++n) _Pragma("unroll") for (int k = 0; k < 2; ++k) \
;         acc[ai][bj][m][n] = __builtin_amdgcn_mfma_f32_16x16x32_bf16(Bt[n][k], At[m][k], acc[ai][bj][m][n], 0, 0, 0); __builtin_amdgcn_s_setprio(0); } while (0)
; #define PG8_WAIT_V(n) asm volatile("s_waitcnt vmcnt(" #n ")" ::: "memory")
; template <class Epi, class Sched>
; __device__ __forceinline__ void gemm_phase(const int tid, LAS unsigned char* lds, const int lda, const int ldb, const int K, const Sched& S, const Epi& E) {
;     ...
;         const bool has_next = S.next(ui + 1, nxt);
;         const char* nA = has_next ? nxt.a : cA; const char* nB = has_next ? nxt.b : cB;
;         for (int t = 0; t < nt; t += 2) {
;             const bool last = (t == nt - 2);
;             const char* a1 = cA + (size_t)(t + 1) * kstep;
;             const char* a2 = last ? nA : cA + (size_t)(t + 2) * kstep; const char* b2 = last ? nB : cB + (size_t)(t + 2) * kstep;
;             const char* a3 = a2 + kstep; const char* b3 = b2 + kstep;
;             PG8_LDB(B0, 0, 0); PG8_LDB(B1, 0, 1); PG8_SCHED; PG8_LDA(At, 0, 0); PG8_STAGE(PG8_SA(1, 1), a1 + hstepA, voffA);
;             PG8_WAIT_V(8); PG8_WAIT_L(0); PG8_BAR; PG8_MMA(0, 0, At, B0); PG8_MMA(0, 1, At, B1); PG8_BAR; PG8_SCHED;
;             PG8_LDA(At, 0, 1); PG8_STAGE(PG8_SB(0, 0), b2, voffB); PG8_STAGE(PG8_SB(0, 1), b2 + hstepB, voffB); PG8_STAGE(PG8_SA(0, 0), a2, voffA);
;             PG8_WAIT_V(8); PG8_WAIT_L(0); PG8_BAR; if (!cur.half) { PG8_MMA(1, 0, At, B0); PG8_MMA(1, 1, At, B1); } PG8_BAR; PG8_SCHED;
.LBB0_894:
	s_andn2_b64 vcc, exec, s[40:41]
	s_cbranch_vccnz .LBB0_902
	s_add_u32 s50, s50, 0x40080
	s_addc_u32 s51, s51, 0
	s_add_u32 s45, s52, 0x100
	s_addc_u32 s64, s53, 0
	s_mov_b32 s52, 0
	s_add_i32 s65, s52, 2
	s_add_u32 s24, s50, 0xfffc0080
	s_addc_u32 s53, s51, -1
	s_add_i32 s66, 0, 0x10000
	s_cmp_eq_u32 s61, s52
	s_cselect_b32 s55, s3, s53
	s_cselect_b32 s54, s2, s24
	v_add_u32_e32 v166, s66, v146
	s_cselect_b32 s53, s39, s64
	s_cselect_b32 s52, s38, s45
	s_add_i32 s24, 0, 0x14000
	ds_read_b128 v[154:157], v166
	ds_read_b128 v[158:161], v166 offset:1024
	ds_read_b128 v[162:165], v166 offset:2048
	ds_read_b128 v[180:183], v166 offset:3072
	v_add_u32_e32 v166, s24, v146
	ds_read_b128 v[184:187], v166
	ds_read_b128 v[190:193], v166 offset:1024
	ds_read_b128 v[194:197], v166 offset:2048
	ds_read_b128 v[204:207], v166 offset:3072
	v_lshl_add_u64 v[166:167], s[50:51], 0, v[136:137]
	s_add_i32 m0, s29, 0xc000
	ds_read_b128 v[208:211], v153
	ds_read_b128 v[212:215], v153 offset:1024
	ds_read_b128 v[216:219], v153 offset:2048
	ds_read_b128 v[220:223], v153 offset:3072
	ds_read_b128 v[224:227], v153 offset:4096
	ds_read_b128 v[228:231], v153 offset:5120
	ds_read_b128 v[232:235], v153 offset:6144
	ds_read_b128 v[236:239], v153 offset:7168
	global_load_lds_dwordx4 v[166:167], off
	v_lshl_add_u64 v[166:167], s[50:51], 0, v[138:139]
	s_add_i32 m0, s29, 0xe000
	s_nop 0
	global_load_lds_dwordx4 v[166:167], off
	s_waitcnt vmcnt(10)
	s_waitcnt lgkmcnt(0)
	s_barrier
	s_setprio 1
	s_waitcnt lgkmcnt(0)
	v_mfma_f32_16x16x32_bf16 v[124:127], v[154:157], v[208:211], 0
	v_mfma_f32_16x16x32_bf16 v[116:119], v[162:165], v[208:211], 0
	v_mfma_f32_16x16x32_bf16 v[108:111], v[154:157], v[216:219], 0
	v_mfma_f32_16x16x32_bf16 v[100:103], v[162:165], v[216:219], 0
	v_mfma_f32_16x16x32_bf16 v[92:95], v[154:157], v[224:227], 0
	v_mfma_f32_16x16x32_bf16 v[84:87], v[162:165], v[224:227], 0
	v_mfma_f32_16x16x32_bf16 v[76:79], v[154:157], v[232:235], 0
	v_mfma_f32_16x16x32_bf16 v[68:71], v[162:165], v[232:235], 0
	v_mfma_f32_16x16x32_bf16 v[124:127], v[158:161], v[212:215], v[124:127]
	v_mfma_f32_16x16x32_bf16 v[116:119], v[180:183], v[212:215], v[116:119]
	v_mfma_f32_16x16x32_bf16 v[108:111], v[158:161], v[220:223], v[108:111]
	v_mfma_f32_16x16x32_bf16 v[100:103], v[180:183], v[220:223], v[100:103]
	v_mfma_f32_16x16x32_bf16 v[92:95], v[158:161], v[228:231], v[92:95]
	v_mfma_f32_16x16x32_bf16 v[84:87], v[180:183], v[228:231], v[84:87]
	v_mfma_f32_16x16x32_bf16 v[76:79], v[158:161], v[236:239], v[76:79]
	v_mfma_f32_16x16x32_bf16 v[68:71], v[180:183], v[236:239], v[68:71]
	s_setprio 0
	s_setprio 1
	v_mfma_f32_16x16x32_bf16 v[120:123], v[184:187], v[208:211], 0
	v_mfma_f32_16x16x32_bf16 v[112:115], v[194:197], v[208:211], 0
	v_mfma_f32_16x16x32_bf16 v[104:107], v[184:187], v[216:219], 0
	v_mfma_f32_16x16x32_bf16 v[96:99], v[194:197], v[216:219], 0
	v_mfma_f32_16x16x32_bf16 v[88:91], v[184:187], v[224:227], 0
	v_mfma_f32_16x16x32_bf16 v[80:83], v[194:197], v[224:227], 0
	v_mfma_f32_16x16x32_bf16 v[72:75], v[184:187], v[232:235], 0
	v_mfma_f32_16x16x32_bf16 v[64:67], v[194:197], v[232:235], 0
	v_mfma_f32_16x16x32_bf16 v[120:123], v[190:193], v[212:215], v[120:123]
	v_mfma_f32_16x16x32_bf16 v[112:115], v[204:207], v[212:215], v[112:115]
	v_mfma_f32_16x16x32_bf16 v[104:107], v[190:193], v[220:223], v[104:107]
	v_mfma_f32_16x16x32_bf16 v[96:99], v[204:207], v[220:223], v[96:99]
	v_mfma_f32_16x16x32_bf16 v[88:91], v[190:193], v[228:231], v[88:91]
	v_mfma_f32_16x16x32_bf16 v[80:83], v[204:207], v[228:231], v[80:83]
	v_mfma_f32_16x16x32_bf16 v[72:75], v[190:193], v[236:239], v[72:75]
	v_mfma_f32_16x16x32_bf16 v[64:67], v[204:207], v[236:239], v[64:67]
	s_setprio 0
	s_barrier
	s_add_i32 s66, s66, s20
	v_lshl_add_u64 v[166:167], s[52:53], 0, v[132:133]
	s_mov_b32 m0, s66
	ds_read_b128 v[208:211], v153 offset:16384
	ds_read_b128 v[212:215], v153 offset:17408
	ds_read_b128 v[216:219], v153 offset:18432
	ds_read_b128 v[220:223], v153 offset:19456
	ds_read_b128 v[224:227], v153 offset:20480
	ds_read_b128 v[228:231], v153 offset:21504
	ds_read_b128 v[232:235], v153 offset:22528
	ds_read_b128 v[236:239], v153 offset:23552
	global_load_lds_dwordx4 v[166:167], off
	s_add_i32 m0, s66, 0x2000
	s_add_u32 s66, s52, 0x40000
	v_lshl_add_u64 v[240:241], s[52:53], 0, v[128:129]
	s_addc_u32 s67, s53, 0
	s_add_i32 s24, s24, s20
	global_load_lds_dwordx4 v[240:241], off
	v_lshl_add_u64 v[242:243], s[66:67], 0, v[132:133]
	s_mov_b32 m0, s24
	v_lshl_add_u64 v[244:245], s[54:55], 0, v[130:131]
	global_load_lds_dwordx4 v[242:243], off
	v_lshl_add_u64 v[242:243], s[66:67], 0, v[128:129]
	s_add_i32 m0, s24, 0x2000
	s_nop 0
	global_load_lds_dwordx4 v[242:243], off
	v_lshl_add_u64 v[242:243], s[54:55], 0, v[134:135]
	s_waitcnt vmcnt(14)
	s_waitcnt lgkmcnt(0)
	s_barrier
; #define PG8_STAGE(bufoff, gbase, voff) do { _Pragma("unroll") for (int _i = 0; _i < 2; ++_i) \
;         __builtin_amdgcn_global_load_lds((const unsigned*)((const char*)(gbase) + (voff)[_i]), (LAS unsigned*)(lds + (bufoff) + ldsw + _i * 8192), 16, 0, 0); } while (0)
; #define PG8_LDA(dst, b, h) do { _Pragma("unroll") for (int m = 0; m < 4; ++m) _Pragma("unroll") for (int k = 0; k < 2; ++k) dst[m][k] = *(const LAS bf16x8*)(lds + PG8_SA(b, h) + aoff + m * 2048 + k * 1024); } while (0)
; #define PG8_LDB(dst, b, h) do { _Pragma("unroll") for (int n = 0; n < 2; ++n) _Pragma("unroll") for (int k = 0; k < 2; ++k) dst[n][k] = *(const LAS bf16x8*)(lds + PG8_SB(b, h) + boff + n * 2048 + k * 1024); } while (0)
; #define PG8_MMA(ai, bj, At, Bt) do { __builtin_amdgcn_s_setprio(1); _Pragma("unroll") for (int m = 0; m < 4; ++m) _Pragma("unroll") for (int n = 0; n < 2; ++n) _Pragma("unroll") for (int k = 0; k < 2; ++k) \
;         acc[ai][bj][m][n] = __builtin_amdgcn_mfma_f32_16x16x32_bf16(Bt[n][k], At[m][k], acc[ai][bj][m][n], 0, 0, 0); __builtin_amdgcn_s_setprio(0); } while (0)
; #define PG8_WAIT_V(n) asm volatile("s_waitcnt vmcnt(" #n ")" ::: "memory")
; #define PG8_WAIT_L(n) asm volatile("s_waitcnt lgkmcnt(" #n ")" ::: "memory")
; #define PG8_BAR __builtin_amdgcn_s_barrier()
; #define PG8_SCHED __builtin_amdgcn_sched_barrier(0)
; template <class Epi, class Sched>
; __device__ __forceinline__ void gemm_phase(const int tid, LAS unsigned char* lds, const int lda, const int ldb, const int K, const Sched& S, const Epi& E) {
;     ...
;             PG8_WAIT_V(8); PG8_WAIT_L(0); PG8_BAR; if (!cur.half) { PG8_MMA(1, 0, At, B0); PG8_MMA(1, 1, At, B1); } PG8_BAR; PG8_SCHED;
;             PG8_LDB(B0, 1, 0); PG8_LDB(B1, 1, 1); PG8_SCHED; PG8_LDA(At, 1, 0); PG8_STAGE(PG8_SA(0, 1), a2 + hstepA, voffA);
;             PG8_WAIT_V(8); PG8_WAIT_L(0); PG8_BAR; PG8_MMA(0, 0, At, B0); PG8_MMA(0, 1, At, B1); PG8_BAR; PG8_SCHED;
	s_setprio 1
	s_waitcnt lgkmcnt(0)
	v_mfma_f32_16x16x32_bf16 v[60:63], v[154:157], v[208:211], 0
	v_mfma_f32_16x16x32_bf16 v[52:55], v[162:165], v[208:211], 0
	v_mfma_f32_16x16x32_bf16 v[44:47], v[154:157], v[216:219], 0
	v_mfma_f32_16x16x32_bf16 v[36:39], v[162:165], v[216:219], 0
	v_mfma_f32_16x16x32_bf16 v[28:31], v[154:157], v[224:227], 0
	v_mfma_f32_16x16x32_bf16 v[20:23], v[162:165], v[224:227], 0
	v_mfma_f32_16x16x32_bf16 v[12:15], v[154:157], v[232:235], 0
	v_mfma_f32_16x16x32_bf16 v[4:7], v[162:165], v[232:235], 0
	v_mfma_f32_16x16x32_bf16 v[60:63], v[158:161], v[212:215], v[60:63]
	v_mfma_f32_16x16x32_bf16 v[52:55], v[180:183], v[212:215], v[52:55]
	v_mfma_f32_16x16x32_bf16 v[44:47], v[158:161], v[220:223], v[44:47]
	v_mfma_f32_16x16x32_bf16 v[36:39], v[180:183], v[220:223], v[36:39]
	v_mfma_f32_16x16x32_bf16 v[28:31], v[158:161], v[228:231], v[28:31]
	v_mfma_f32_16x16x32_bf16 v[20:23], v[180:183], v[228:231], v[20:23]
	v_mfma_f32_16x16x32_bf16 v[12:15], v[158:161], v[236:239], v[12:15]
	v_mfma_f32_16x16x32_bf16 v[4:7], v[180:183], v[236:239], v[4:7]
	s_setprio 0
	s_setprio 1
	v_mfma_f32_16x16x32_bf16 v[56:59], v[184:187], v[208:211], 0
	v_mfma_f32_16x16x32_bf16 v[48:51], v[194:197], v[208:211], 0
	v_mfma_f32_16x16x32_bf16 v[40:43], v[184:187], v[216:219], 0
	v_mfma_f32_16x16x32_bf16 v[32:35], v[194:197], v[216:219], 0
	v_mfma_f32_16x16x32_bf16 v[24:27], v[184:187], v[224:227], 0
	v_mfma_f32_16x16x32_bf16 v[16:19], v[194:197], v[224:227], 0
	v_mfma_f32_16x16x32_bf16 v[8:11], v[184:187], v[232:235], 0
	v_mfma_f32_16x16x32_bf16 v[0:3], v[194:197], v[232:235], 0
	v_mfma_f32_16x16x32_bf16 v[56:59], v[190:193], v[212:215], v[56:59]
	v_mfma_f32_16x16x32_bf16 v[48:51], v[204:207], v[212:215], v[48:51]
	v_mfma_f32_16x16x32_bf16 v[40:43], v[190:193], v[220:223], v[40:43]
	v_mfma_f32_16x16x32_bf16 v[32:35], v[204:207], v[220:223], v[32:35]
	v_mfma_f32_16x16x32_bf16 v[24:27], v[190:193], v[228:231], v[24:27]
	v_mfma_f32_16x16x32_bf16 v[16:19], v[204:207], v[228:231], v[16:19]
	v_mfma_f32_16x16x32_bf16 v[8:11], v[190:193], v[236:239], v[8:11]
	v_mfma_f32_16x16x32_bf16 v[0:3], v[204:207], v[236:239], v[0:3]
	s_setprio 0
	s_barrier
	s_add_i32 s24, 0, 0x18000
	v_add_u32_e32 v176, s24, v146
	s_add_i32 s66, 0, 0x1c000
	ds_read_b128 v[154:157], v176
	ds_read_b128 v[158:161], v176 offset:1024
	ds_read_b128 v[162:165], v176 offset:2048
	ds_read_b128 v[180:183], v176 offset:3072
	v_add_u32_e32 v176, s66, v146
	ds_read_b128 v[184:187], v176
	ds_read_b128 v[190:193], v176 offset:1024
	ds_read_b128 v[194:197], v176 offset:2048
	ds_read_b128 v[204:207], v176 offset:3072
	s_mov_b32 m0, s29
	s_nop 0
	global_load_lds_dwordx4 v[242:243], off
	s_mov_b32 m0, s31
	s_nop 0
	global_load_lds_dwordx4 v[244:245], off
	s_add_u32 s54, s54, 0x40000
	s_addc_u32 s55, s55, 0
	s_mov_b32 m0, s56
	v_lshl_add_u64 v[246:247], s[54:55], 0, v[134:135]
	ds_read_b128 v[208:211], v153 offset:32768
	ds_read_b128 v[212:215], v153 offset:33792
	ds_read_b128 v[216:219], v153 offset:34816
	ds_read_b128 v[220:223], v153 offset:35840
	ds_read_b128 v[224:227], v153 offset:36864
	ds_read_b128 v[228:231], v153 offset:37888
	ds_read_b128 v[232:235], v153 offset:38912
	ds_read_b128 v[236:239], v153 offset:39936
	global_load_lds_dwordx4 v[246:247], off
	v_lshl_add_u64 v[246:247], s[54:55], 0, v[130:131]
	s_mov_b32 m0, s57
	s_nop 0
	global_load_lds_dwordx4 v[246:247], off
	s_waitcnt vmcnt(8)
	s_waitcnt lgkmcnt(0)
	s_barrier
	s_setprio 1
	s_waitcnt lgkmcnt(0)
	v_mfma_f32_16x16x32_bf16 v[124:127], v[154:157], v[208:211], v[124:127]
	v_mfma_f32_16x16x32_bf16 v[116:119], v[162:165], v[208:211], v[116:119]
	v_mfma_f32_16x16x32_bf16 v[108:111], v[154:157], v[216:219], v[108:111]
	v_mfma_f32_16x16x32_bf16 v[100:103], v[162:165], v[216:219], v[100:103]
	v_mfma_f32_16x16x32_bf16 v[92:95], v[154:157], v[224:227], v[92:95]
	v_mfma_f32_16x16x32_bf16 v[84:87], v[162:165], v[224:227], v[84:87]
	v_mfma_f32_16x16x32_bf16 v[76:79], v[154:157], v[232:235], v[76:79]
	v_mfma_f32_16x16x32_bf16 v[68:71], v[162:165], v[232:235], v[68:71]
	v_mfma_f32_16x16x32_bf16 v[124:127], v[158:161], v[212:215], v[124:127]
	v_mfma_f32_16x16x32_bf16 v[116:119], v[180:183], v[212:215], v[116:119]
	v_mfma_f32_16x16x32_bf16 v[108:111], v[158:161], v[220:223], v[108:111]
	v_mfma_f32_16x16x32_bf16 v[100:103], v[180:183], v[220:223], v[100:103]
	v_mfma_f32_16x16x32_bf16 v[92:95], v[158:161], v[228:231], v[92:95]
	v_mfma_f32_16x16x32_bf16 v[84:87], v[180:183], v[228:231], v[84:87]
	v_mfma_f32_16x16x32_bf16 v[76:79], v[158:161], v[236:239], v[76:79]
	v_mfma_f32_16x16x32_bf16 v[68:71], v[180:183], v[236:239], v[68:71]
	s_setprio 0
	s_setprio 1
	v_mfma_f32_16x16x32_bf16 v[120:123], v[184:187], v[208:211], v[120:123]
	v_mfma_f32_16x16x32_bf16 v[112:115], v[194:197], v[208:211], v[112:115]
	v_mfma_f32_16x16x32_bf16 v[104:107], v[184:187], v[216:219], v[104:107]
	v_mfma_f32_16x16x32_bf16 v[96:99], v[194:197], v[216:219], v[96:99]
	v_mfma_f32_16x16x32_bf16 v[88:91], v[184:187], v[224:227], v[88:91]
	v_mfma_f32_16x16x32_bf16 v[80:83], v[194:197], v[224:227], v[80:83]
	v_mfma_f32_16x16x32_bf16 v[72:75], v[184:187], v[232:235], v[72:75]
	v_mfma_f32_16x16x32_bf16 v[64:67], v[194:197], v[232:235], v[64:67]
	v_mfma_f32_16x16x32_bf16 v[120:123], v[190:193], v[212:215], v[120:123]
	v_mfma_f32_16x16x32_bf16 v[112:115], v[204:207], v[212:215], v[112:115]
	v_mfma_f32_16x16x32_bf16 v[104:107], v[190:193], v[220:223], v[104:107]
	v_mfma_f32_16x16x32_bf16 v[96:99], v[204:207], v[220:223], v[96:99]
	v_mfma_f32_16x16x32_bf16 v[88:91], v[190:193], v[228:231], v[88:91]
	v_mfma_f32_16x16x32_bf16 v[80:83], v[204:207], v[228:231], v[80:83]
	v_mfma_f32_16x16x32_bf16 v[72:75], v[190:193], v[236:239], v[72:75]
	v_mfma_f32_16x16x32_bf16 v[64:67], v[204:207], v[236:239], v[64:67]
	s_setprio 0
	s_barrier
; #define PG8_STAGE(bufoff, gbase, voff) do { _Pragma("unroll") for (int _i = 0; _i < 2; ++_i) \
;         __builtin_amdgcn_global_load_lds((const unsigned*)((const char*)(gbase) + (voff)[_i]), (LAS unsigned*)(lds + (bufoff) + ldsw + _i * 8192), 16, 0, 0); } while (0)
; #define PG8_LDA(dst, b, h) do { _Pragma("unroll") for (int m = 0; m < 4; ++m) _Pragma("unroll") for (int k = 0; k < 2; ++k) dst[m][k] = *(const LAS bf16x8*)(lds + PG8_SA(b, h) + aoff + m * 2048 + k * 1024); } while (0)
; #define PG8_MMA(ai, bj, At, Bt) do { __builtin_amdgcn_s_setprio(1); _Pragma("unroll") for (int m = 0; m < 4; ++m) _Pragma("unroll") for (int n = 0; n < 2; ++n) _Pragma("unroll") for (int k = 0; k < 2; ++k) \
;         acc[ai][bj][m][n] = __builtin_amdgcn_mfma_f32_16x16x32_bf16(Bt[n][k], At[m][k], acc[ai][bj][m][n], 0, 0, 0); __builtin_amdgcn_s_setprio(0); } while (0)
; #define PG8_WAIT_V(n) asm volatile("s_waitcnt vmcnt(" #n ")" ::: "memory")
; #define PG8_WAIT_L(n) asm volatile("s_waitcnt lgkmcnt(" #n ")" ::: "memory")
; #define PG8_BAR __builtin_amdgcn_s_barrier()
; #define PG8_SCHED __builtin_amdgcn_sched_barrier(0)
; template <class Epi, class Sched>
; __device__ __forceinline__ void gemm_phase(const int tid, LAS unsigned char* lds, const int lda, const int ldb, const int K, const Sched& S, const Epi& E) {
;     ...
;             PG8_LDA(At, 1, 1); PG8_STAGE(PG8_SB(1, 0), b3, voffB); PG8_STAGE(PG8_SB(1, 1), b3 + hstepB, voffB); PG8_STAGE(PG8_SA(1, 0), a3, voffA);
;             PG8_WAIT_V(8); PG8_WAIT_L(0); PG8_BAR; if (!cur.half) { PG8_MMA(1, 0, At, B0); PG8_MMA(1, 1, At, B1); } PG8_BAR; PG8_SCHED;
;         }
	s_add_i32 s24, s24, s20
	v_lshl_add_u64 v[166:167], v[166:167], 0, s[6:7]
	s_mov_b32 m0, s24
	ds_read_b128 v[208:211], v153 offset:49152
	ds_read_b128 v[212:215], v153 offset:50176
	ds_read_b128 v[216:219], v153 offset:51200
	ds_read_b128 v[220:223], v153 offset:52224
	ds_read_b128 v[224:227], v153 offset:53248
	ds_read_b128 v[228:231], v153 offset:54272
	ds_read_b128 v[232:235], v153 offset:55296
	ds_read_b128 v[236:239], v153 offset:56320
	global_load_lds_dwordx4 v[166:167], off
	s_add_i32 m0, s24, 0x2000
	s_add_u32 s52, s52, 0x40080
	v_lshl_add_u64 v[166:167], v[240:241], 0, s[6:7]
	s_addc_u32 s53, s53, 0
	s_add_i32 s24, s66, s20
	global_load_lds_dwordx4 v[166:167], off
	v_lshl_add_u64 v[166:167], s[52:53], 0, v[132:133]
	s_mov_b32 m0, s24
	s_nop 0
	global_load_lds_dwordx4 v[166:167], off
	v_lshl_add_u64 v[166:167], s[52:53], 0, v[128:129]
	s_add_i32 m0, s24, 0x2000
	s_nop 0
	global_load_lds_dwordx4 v[166:167], off
	v_lshl_add_u64 v[166:167], v[242:243], 0, s[6:7]
	s_mov_b32 m0, s58
	s_nop 0
	global_load_lds_dwordx4 v[166:167], off
	v_lshl_add_u64 v[166:167], v[244:245], 0, s[6:7]
	s_mov_b32 m0, s59
	s_nop 0
	global_load_lds_dwordx4 v[166:167], off
	s_waitcnt vmcnt(8)
	s_waitcnt lgkmcnt(0)
	s_barrier
	s_setprio 1
	s_waitcnt lgkmcnt(0)
	v_mfma_f32_16x16x32_bf16 v[60:63], v[154:157], v[208:211], v[60:63]
	v_mfma_f32_16x16x32_bf16 v[52:55], v[162:165], v[208:211], v[52:55]
	v_mfma_f32_16x16x32_bf16 v[44:47], v[154:157], v[216:219], v[44:47]
	v_mfma_f32_16x16x32_bf16 v[36:39], v[162:165], v[216:219], v[36:39]
	v_mfma_f32_16x16x32_bf16 v[28:31], v[154:157], v[224:227], v[28:31]
	v_mfma_f32_16x16x32_bf16 v[20:23], v[162:165], v[224:227], v[20:23]
	v_mfma_f32_16x16x32_bf16 v[12:15], v[154:157], v[232:235], v[12:15]
	v_mfma_f32_16x16x32_bf16 v[4:7], v[162:165], v[232:235], v[4:7]
	v_mfma_f32_16x16x32_bf16 v[60:63], v[158:161], v[212:215], v[60:63]
	v_mfma_f32_16x16x32_bf16 v[52:55], v[180:183], v[212:215], v[52:55]
	v_mfma_f32_16x16x32_bf16 v[44:47], v[158:161], v[220:223], v[44:47]
	v_mfma_f32_16x16x32_bf16 v[36:39], v[180:183], v[220:223], v[36:39]
	v_mfma_f32_16x16x32_bf16 v[28:31], v[158:161], v[228:231], v[28:31]
	v_mfma_f32_16x16x32_bf16 v[20:23], v[180:183], v[228:231], v[20:23]
	v_mfma_f32_16x16x32_bf16 v[12:15], v[158:161], v[236:239], v[12:15]
	v_mfma_f32_16x16x32_bf16 v[4:7], v[180:183], v[236:239], v[4:7]
	s_setprio 0
	s_setprio 1
	v_mfma_f32_16x16x32_bf16 v[56:59], v[184:187], v[208:211], v[56:59]
	v_mfma_f32_16x16x32_bf16 v[48:51], v[194:197], v[208:211], v[48:51]
	v_mfma_f32_16x16x32_bf16 v[40:43], v[184:187], v[216:219], v[40:43]
	v_mfma_f32_16x16x32_bf16 v[32:35], v[194:197], v[216:219], v[32:35]
	v_mfma_f32_16x16x32_bf16 v[24:27], v[184:187], v[224:227], v[24:27]
	v_mfma_f32_16x16x32_bf16 v[16:19], v[194:197], v[224:227], v[16:19]
	v_mfma_f32_16x16x32_bf16 v[8:11], v[184:187], v[232:235], v[8:11]
	v_mfma_f32_16x16x32_bf16 v[0:3], v[194:197], v[232:235], v[0:3]
	v_mfma_f32_16x16x32_bf16 v[56:59], v[190:193], v[212:215], v[56:59]
	v_mfma_f32_16x16x32_bf16 v[48:51], v[204:207], v[212:215], v[48:51]
	v_mfma_f32_16x16x32_bf16 v[40:43], v[190:193], v[220:223], v[40:43]
	v_mfma_f32_16x16x32_bf16 v[32:35], v[204:207], v[220:223], v[32:35]
	v_mfma_f32_16x16x32_bf16 v[24:27], v[190:193], v[228:231], v[24:27]
	v_mfma_f32_16x16x32_bf16 v[16:19], v[204:207], v[228:231], v[16:19]
	v_mfma_f32_16x16x32_bf16 v[8:11], v[190:193], v[236:239], v[8:11]
	v_mfma_f32_16x16x32_bf16 v[0:3], v[204:207], v[236:239], v[0:3]
	s_setprio 0
	s_barrier
	s_add_u32 s50, s50, 0x100
	s_addc_u32 s51, s51, 0
	s_add_u32 s45, s45, 0x100
	s_addc_u32 s64, s64, 0
	s_cmp_ge_i32 s65, s13
	s_mov_b32 s52, s65
	s_cbranch_scc1 .Lkexit_896
